# v082 with the attention step's last pre-barrier exp/sum group moved behind the mid-step barrier (QK group ends on its MFMA, then the first PV MFMA, then the barrier)
# baseline (speedup 1.0000x reference)
.Lattn_fx_skipw1:
	v_exp_f32_e32 v78, v78
	v_exp_f32_e32 v79, v79
	v_add_f32_e32 v246, v76, v246
	v_add_f32_e32 v246, v77, v246
	v_cvt_pk_bf16_f32 v71, v76, v77
	v_mfma_f32_32x32x16_bf16 v[98:113], v[186:189], v[138:141], v[98:113]
	v_exp_f32_e32 v80, v80
	v_exp_f32_e32 v81, v81
	v_add_f32_e32 v246, v78, v246
	v_add_f32_e32 v246, v79, v246
	v_cvt_pk_bf16_f32 v72, v78, v79
	v_mfma_f32_32x32x16_bf16 v[114:129], v[174:177], v[142:145], v[114:129]
	v_exp_f32_e32 v34, v34
	v_exp_f32_e32 v35, v35
	v_add_f32_e32 v246, v80, v246
	v_add_f32_e32 v246, v81, v246
	v_cvt_pk_bf16_f32 v73, v80, v81
	v_mfma_f32_32x32x16_bf16 v[98:113], v[82:85], v[142:145], v[98:113]
	s_waitcnt lgkmcnt(0)
	v_mfma_f32_32x32x16_bf16 v[18:33], v[86:89], v[66:69], v[18:33]
	s_barrier
	ds_read_b128 v[162:165], v193 offset:18432
	ds_read_b128 v[178:181], v193 offset:23040
	v_exp_f32_e32 v36, v36
	v_exp_f32_e32 v37, v37
	v_add_f32_e32 v247, v34, v35
	v_cvt_pk_bf16_f32 v74, v34, v35
	v_exp_f32_e32 v38, v38
	v_exp_f32_e32 v39, v39
	v_add_f32_e32 v247, v36, v247
	v_add_f32_e32 v247, v37, v247
	v_cvt_pk_bf16_f32 v75, v36, v37
	v_mfma_f32_32x32x16_bf16 v[2:17], v[216:219], v[66:69], v[2:17]
	ds_read_b128 v[166:169], v193 offset:18464
	ds_read_b128 v[182:185], v193 offset:23072
	v_exp_f32_e32 v40, v40
	v_exp_f32_e32 v41, v41
	v_add_f32_e32 v247, v38, v247
	v_add_f32_e32 v247, v39, v247
	v_cvt_pk_bf16_f32 v76, v38, v39
	v_mfma_f32_32x32x16_bf16 v[18:33], v[90:93], v[70:73], v[18:33]
	ds_read_b128 v[170:173], v193 offset:18496
	ds_read_b128 v[186:189], v193 offset:23104
	v_exp_f32_e32 v42, v42
	v_exp_f32_e32 v43, v43
	v_add_f32_e32 v247, v40, v247
	v_add_f32_e32 v247, v41, v247
	v_cvt_pk_bf16_f32 v77, v40, v41
	v_mfma_f32_32x32x16_bf16 v[2:17], v[220:223], v[70:73], v[2:17]
	ds_read_b128 v[174:177], v193 offset:18528
	ds_read_b128 v[82:85], v193 offset:23136
	v_exp_f32_e32 v44, v44
	v_exp_f32_e32 v45, v45
	v_add_f32_e32 v247, v42, v247
	v_add_f32_e32 v247, v43, v247
	v_cvt_pk_bf16_f32 v78, v42, v43
	v_mfma_f32_32x32x16_bf16 v[18:33], v[94:97], v[74:77], v[18:33]
	v_exp_f32_e32 v46, v46
	v_exp_f32_e32 v47, v47
	v_add_f32_e32 v247, v44, v247
	v_add_f32_e32 v247, v45, v247
	v_cvt_pk_bf16_f32 v79, v44, v45
	v_mfma_f32_32x32x16_bf16 v[2:17], v[224:227], v[74:77], v[2:17]
	v_exp_f32_e32 v48, v48
	v_exp_f32_e32 v49, v49
	v_add_f32_e32 v247, v46, v247
	v_add_f32_e32 v247, v47, v247
	v_cvt_pk_bf16_f32 v80, v46, v47
	v_cvt_pk_bf16_f32 v81, v48, v49
	v_add_f32_e32 v247, v48, v247
	v_add_f32_e32 v247, v49, v247
	v_mfma_f32_32x32x16_bf16 v[18:33], v[212:215], v[78:81], v[18:33]
	v_mfma_f32_32x32x16_bf16 v[2:17], v[242:245], v[78:81], v[2:17]
	v_add_f32_e32 v210, v210, v246
	v_add_f32_e32 v210, v210, v247
	s_min_i32 s24, s10, s58
	s_mul_i32 s44, s24, 0xa0000
	s_add_u32 s44, s3, s44
	s_addc_u32 s45, s12, 0
	s_lshl_b32 s46, s24, 7
	s_add_u32 s46, s15, s46
	s_addc_u32 s47, s23, 0
	global_load_dwordx4 v[146:149], v252, s[44:45] offset:1024
	global_load_dwordx4 v[150:153], v253, s[46:47]
	v_exp_f32_e32 v114, v114
	v_exp_f32_e32 v115, v115
	v_exp_f32_e32 v116, v116
	v_exp_f32_e32 v117, v117
	v_add_f32_e32 v246, v114, v115
	v_cvt_pk_bf16_f32 v114, v114, v115
	s_waitcnt lgkmcnt(0)
	v_mfma_f32_32x32x16_bf16 v[66:81], v[162:165], v[130:133], v[50:65]
	ds_read_b128 v[86:89], v248
	ds_read_b128 v[216:219], v248 offset:4608
	v_exp_f32_e32 v118, v118
	v_exp_f32_e32 v119, v119
	v_add_f32_e32 v246, v116, v246
	v_add_f32_e32 v246, v117, v246
	v_cvt_pk_bf16_f32 v115, v116, v117
	v_mfma_f32_32x32x16_bf16 v[34:49], v[178:181], v[130:133], v[50:65]
	ds_read_b128 v[90:93], v248 offset:32
	ds_read_b128 v[220:223], v248 offset:4640
	v_exp_f32_e32 v120, v120
	v_exp_f32_e32 v121, v121
	v_add_f32_e32 v246, v118, v246
	v_add_f32_e32 v246, v119, v246
	v_cvt_pk_bf16_f32 v116, v118, v119
	v_mfma_f32_32x32x16_bf16 v[66:81], v[166:169], v[134:137], v[66:81]
	ds_read_b128 v[94:97], v248 offset:64
	ds_read_b128 v[224:227], v248 offset:4672
	v_exp_f32_e32 v122, v122
	v_exp_f32_e32 v123, v123
	v_add_f32_e32 v246, v120, v246
	v_add_f32_e32 v246, v121, v246
	v_cvt_pk_bf16_f32 v117, v120, v121
	v_mfma_f32_32x32x16_bf16 v[34:49], v[182:185], v[134:137], v[34:49]
	ds_read_b128 v[212:215], v248 offset:96
	ds_read_b128 v[242:245], v248 offset:4704
	v_exp_f32_e32 v124, v124
	v_exp_f32_e32 v125, v125
	v_add_f32_e32 v246, v122, v246
	v_add_f32_e32 v246, v123, v246
	v_cvt_pk_bf16_f32 v118, v122, v123
	v_mfma_f32_32x32x16_bf16 v[66:81], v[170:173], v[138:141], v[66:81]
	s_cmp_ge_u32 s11, s16
	s_cbranch_scc1 .Lattn_fx_skipw2
	s_waitcnt vmcnt(2)
	ds_write_b128 v192, v[154:157] offset:55296
	ds_write_b128 v204, v[158:161] offset:64512
.Lattn_fx_skipw2:
	v_exp_f32_e32 v126, v126
	v_exp_f32_e32 v127, v127
	v_add_f32_e32 v246, v124, v246
	v_add_f32_e32 v246, v125, v246
	v_cvt_pk_bf16_f32 v119, v124, v125
	v_mfma_f32_32x32x16_bf16 v[34:49], v[186:189], v[138:141], v[34:49]
	v_exp_f32_e32 v128, v128
	v_exp_f32_e32 v129, v129
	v_add_f32_e32 v246, v126, v246
	v_add_f32_e32 v246, v127, v246
	v_cvt_pk_bf16_f32 v120, v126, v127
	v_mfma_f32_32x32x16_bf16 v[66:81], v[174:177], v[142:145], v[66:81]
	v_exp_f32_e32 v98, v98
	v_exp_f32_e32 v99, v99
	v_add_f32_e32 v246, v128, v246
	v_add_f32_e32 v246, v129, v246
	v_cvt_pk_bf16_f32 v121, v128, v129
	v_mfma_f32_32x32x16_bf16 v[34:49], v[82:85], v[142:145], v[34:49]
	s_waitcnt lgkmcnt(0)
	v_mfma_f32_32x32x16_bf16 v[18:33], v[86:89], v[114:117], v[18:33]
	s_barrier
	ds_read_b128 v[162:165], v193 offset:55296
	ds_read_b128 v[178:181], v193 offset:59904
	v_exp_f32_e32 v100, v100
	v_exp_f32_e32 v101, v101
	v_add_f32_e32 v247, v98, v99
	v_cvt_pk_bf16_f32 v122, v98, v99
	v_exp_f32_e32 v102, v102
	v_exp_f32_e32 v103, v103
	v_add_f32_e32 v247, v100, v247
	v_add_f32_e32 v247, v101, v247
	v_cvt_pk_bf16_f32 v123, v100, v101
	v_mfma_f32_32x32x16_bf16 v[2:17], v[216:219], v[114:117], v[2:17]
	ds_read_b128 v[166:169], v193 offset:55328
	ds_read_b128 v[182:185], v193 offset:59936
	v_exp_f32_e32 v104, v104
	v_exp_f32_e32 v105, v105
	v_add_f32_e32 v247, v102, v247
	v_add_f32_e32 v247, v103, v247
	v_cvt_pk_bf16_f32 v124, v102, v103
	v_mfma_f32_32x32x16_bf16 v[18:33], v[90:93], v[118:121], v[18:33]
	ds_read_b128 v[170:173], v193 offset:55360
	ds_read_b128 v[186:189], v193 offset:59968
	v_exp_f32_e32 v106, v106
	v_exp_f32_e32 v107, v107
	v_add_f32_e32 v247, v104, v247
	v_add_f32_e32 v247, v105, v247
	v_cvt_pk_bf16_f32 v125, v104, v105
	v_mfma_f32_32x32x16_bf16 v[2:17], v[220:223], v[118:121], v[2:17]
	ds_read_b128 v[174:177], v193 offset:55392
	ds_read_b128 v[82:85], v193 offset:60000
	v_exp_f32_e32 v108, v108
	v_exp_f32_e32 v109, v109
	v_add_f32_e32 v247, v106, v247
	v_add_f32_e32 v247, v107, v247
	v_cvt_pk_bf16_f32 v126, v106, v107
	v_mfma_f32_32x32x16_bf16 v[18:33], v[94:97], v[122:125], v[18:33]
	v_exp_f32_e32 v110, v110
	v_exp_f32_e32 v111, v111
	v_add_f32_e32 v247, v108, v247
	v_add_f32_e32 v247, v109, v247
	v_cvt_pk_bf16_f32 v127, v108, v109
	v_mfma_f32_32x32x16_bf16 v[2:17], v[224:227], v[122:125], v[2:17]
	v_exp_f32_e32 v112, v112
	v_exp_f32_e32 v113, v113
	v_add_f32_e32 v247, v110, v247
	v_add_f32_e32 v247, v111, v247
	v_cvt_pk_bf16_f32 v128, v110, v111
	v_cvt_pk_bf16_f32 v129, v112, v113
	v_add_f32_e32 v247, v112, v247
	v_add_f32_e32 v247, v113, v247
	v_mfma_f32_32x32x16_bf16 v[18:33], v[212:215], v[126:129], v[18:33]
	v_mfma_f32_32x32x16_bf16 v[2:17], v[242:245], v[126:129], v[2:17]
	v_add_f32_e32 v210, v210, v246
	v_add_f32_e32 v210, v210, v247
	s_add_i32 s10, s10, 2
	s_cmp_lt_u32 s11, s16
	s_cbranch_scc0 .Lattn_fx_exit0
	s_add_i32 s11, s10, -1
	s_min_i32 s1, s11, s58
	s_mul_i32 s44, s1, 0xa0000
	s_add_u32 s44, s3, s44
	s_addc_u32 s45, s12, 0
	s_lshl_b32 s46, s1, 7
	s_add_u32 s46, s15, s46
	s_addc_u32 s47, s23, 0
	s_add_i32 s24, s10, -2
	s_cmp_lt_u32 s24, s16
	s_cselect_b64 s[0:1], -1, 0
	global_load_dwordx4 v[154:157], v252, s[44:45] offset:1024
	global_load_dwordx4 v[158:161], v253, s[46:47]
	v_exp_f32_e32 v66, v66
	v_exp_f32_e32 v67, v67
	v_exp_f32_e32 v68, v68
	v_exp_f32_e32 v69, v69
	v_add_f32_e32 v246, v66, v67
	v_cvt_pk_bf16_f32 v66, v66, v67
	s_waitcnt lgkmcnt(0)
	v_mfma_f32_32x32x16_bf16 v[114:129], v[162:165], v[130:133], v[50:65]
	ds_read_b128 v[86:89], v248 offset:18432
	ds_read_b128 v[216:219], v248 offset:23040
	v_exp_f32_e32 v70, v70
	v_exp_f32_e32 v71, v71
	v_add_f32_e32 v246, v68, v246
	v_add_f32_e32 v246, v69, v246
	v_cvt_pk_bf16_f32 v67, v68, v69
	v_mfma_f32_32x32x16_bf16 v[98:113], v[178:181], v[130:133], v[50:65]
	ds_read_b128 v[90:93], v248 offset:18464
	ds_read_b128 v[220:223], v248 offset:23072
	v_exp_f32_e32 v72, v72
	v_exp_f32_e32 v73, v73
	v_add_f32_e32 v246, v70, v246
	v_add_f32_e32 v246, v71, v246
	v_cvt_pk_bf16_f32 v68, v70, v71
	v_mfma_f32_32x32x16_bf16 v[114:129], v[166:169], v[134:137], v[114:129]
	ds_read_b128 v[94:97], v248 offset:18496
	ds_read_b128 v[224:227], v248 offset:23104
	v_exp_f32_e32 v74, v74
	v_exp_f32_e32 v75, v75
	v_add_f32_e32 v246, v72, v246
	v_add_f32_e32 v246, v73, v246
	v_cvt_pk_bf16_f32 v69, v72, v73
	v_mfma_f32_32x32x16_bf16 v[98:113], v[182:185], v[134:137], v[98:113]
	ds_read_b128 v[212:215], v248 offset:18528
	ds_read_b128 v[242:245], v248 offset:23136
	v_exp_f32_e32 v76, v76
	v_exp_f32_e32 v77, v77
	v_add_f32_e32 v246, v74, v246
	v_add_f32_e32 v246, v75, v246
	v_cvt_pk_bf16_f32 v70, v74, v75
	v_mfma_f32_32x32x16_bf16 v[114:129], v[170:173], v[138:141], v[114:129]
	s_cmp_ge_u32 s24, s16
	s_cbranch_scc1 .Lattn_fx_skipw3
	s_waitcnt vmcnt(2)
	ds_write_b128 v192, v[146:149] offset:36864
	ds_write_b128 v204, v[150:153] offset:46080
.Lattn_fx_skipw3:
	v_exp_f32_e32 v78, v78
	v_exp_f32_e32 v79, v79
	v_add_f32_e32 v246, v76, v246
	v_add_f32_e32 v246, v77, v246
	v_cvt_pk_bf16_f32 v71, v76, v77
	v_mfma_f32_32x32x16_bf16 v[98:113], v[186:189], v[138:141], v[98:113]
	v_exp_f32_e32 v80, v80
	v_exp_f32_e32 v81, v81
	v_add_f32_e32 v246, v78, v246
	v_add_f32_e32 v246, v79, v246
	v_cvt_pk_bf16_f32 v72, v78, v79
	v_mfma_f32_32x32x16_bf16 v[114:129], v[174:177], v[142:145], v[114:129]
	v_exp_f32_e32 v34, v34
	v_exp_f32_e32 v35, v35
	v_add_f32_e32 v246, v80, v246
	v_add_f32_e32 v246, v81, v246
	v_cvt_pk_bf16_f32 v73, v80, v81
	v_mfma_f32_32x32x16_bf16 v[98:113], v[82:85], v[142:145], v[98:113]
	s_waitcnt lgkmcnt(0)
	v_mfma_f32_32x32x16_bf16 v[18:33], v[86:89], v[66:69], v[18:33]
	s_barrier
	ds_read_b128 v[162:165], v193 offset:36864
	ds_read_b128 v[178:181], v193 offset:41472
	v_exp_f32_e32 v36, v36
	v_exp_f32_e32 v37, v37
	v_add_f32_e32 v247, v34, v35
	v_cvt_pk_bf16_f32 v74, v34, v35
	v_exp_f32_e32 v38, v38
	v_exp_f32_e32 v39, v39
	v_add_f32_e32 v247, v36, v247
	v_add_f32_e32 v247, v37, v247
	v_cvt_pk_bf16_f32 v75, v36, v37
	v_mfma_f32_32x32x16_bf16 v[2:17], v[216:219], v[66:69], v[2:17]
	ds_read_b128 v[166:169], v193 offset:36896
	ds_read_b128 v[182:185], v193 offset:41504
	v_exp_f32_e32 v40, v40
	v_exp_f32_e32 v41, v41
	v_add_f32_e32 v247, v38, v247
	v_add_f32_e32 v247, v39, v247
	v_cvt_pk_bf16_f32 v76, v38, v39
	v_mfma_f32_32x32x16_bf16 v[18:33], v[90:93], v[70:73], v[18:33]
	ds_read_b128 v[170:173], v193 offset:36928
	ds_read_b128 v[186:189], v193 offset:41536
	v_exp_f32_e32 v42, v42
	v_exp_f32_e32 v43, v43
	v_add_f32_e32 v247, v40, v247
	v_add_f32_e32 v247, v41, v247
	v_cvt_pk_bf16_f32 v77, v40, v41
	v_mfma_f32_32x32x16_bf16 v[2:17], v[220:223], v[70:73], v[2:17]
	ds_read_b128 v[174:177], v193 offset:36960
	ds_read_b128 v[82:85], v193 offset:41568
	v_exp_f32_e32 v44, v44
	v_exp_f32_e32 v45, v45
	v_add_f32_e32 v247, v42, v247
	v_add_f32_e32 v247, v43, v247
	v_cvt_pk_bf16_f32 v78, v42, v43
	v_mfma_f32_32x32x16_bf16 v[18:33], v[94:97], v[74:77], v[18:33]
	v_exp_f32_e32 v46, v46
	v_exp_f32_e32 v47, v47
	v_add_f32_e32 v247, v44, v247
	v_add_f32_e32 v247, v45, v247
	v_cvt_pk_bf16_f32 v79, v44, v45
	v_mfma_f32_32x32x16_bf16 v[2:17], v[224:227], v[74:77], v[2:17]
	v_exp_f32_e32 v48, v48
	v_exp_f32_e32 v49, v49
	v_add_f32_e32 v247, v46, v247
	v_add_f32_e32 v247, v47, v247
	v_cvt_pk_bf16_f32 v80, v46, v47
	v_cvt_pk_bf16_f32 v81, v48, v49
	v_add_f32_e32 v247, v48, v247
	v_add_f32_e32 v247, v49, v247
	v_mfma_f32_32x32x16_bf16 v[18:33], v[212:215], v[78:81], v[18:33]
	v_mfma_f32_32x32x16_bf16 v[2:17], v[242:245], v[78:81], v[2:17]
	v_add_f32_e32 v210, v210, v246
	v_add_f32_e32 v210, v210, v247
	s_min_i32 s24, s10, s58
	s_mul_i32 s44, s24, 0xa0000
	s_add_u32 s44, s3, s44
	s_addc_u32 s45, s12, 0
	s_lshl_b32 s46, s24, 7
	s_add_u32 s46, s15, s46
	s_addc_u32 s47, s23, 0
	global_load_dwordx4 v[146:149], v252, s[44:45] offset:1024
	global_load_dwordx4 v[150:153], v253, s[46:47]
	v_exp_f32_e32 v114, v114
	v_exp_f32_e32 v115, v115
	v_exp_f32_e32 v116, v116
	v_exp_f32_e32 v117, v117
	v_add_f32_e32 v246, v114, v115
	v_cvt_pk_bf16_f32 v114, v114, v115
	s_waitcnt lgkmcnt(0)
	v_mfma_f32_32x32x16_bf16 v[66:81], v[162:165], v[130:133], v[50:65]
	ds_read_b128 v[86:89], v248 offset:55296
	ds_read_b128 v[216:219], v248 offset:59904
	v_exp_f32_e32 v118, v118
	v_exp_f32_e32 v119, v119
	v_add_f32_e32 v246, v116, v246
	v_add_f32_e32 v246, v117, v246
	v_cvt_pk_bf16_f32 v115, v116, v117
	v_mfma_f32_32x32x16_bf16 v[34:49], v[178:181], v[130:133], v[50:65]
	ds_read_b128 v[90:93], v248 offset:55328
	ds_read_b128 v[220:223], v248 offset:59936
	v_exp_f32_e32 v120, v120
	v_exp_f32_e32 v121, v121
	v_add_f32_e32 v246, v118, v246
	v_add_f32_e32 v246, v119, v246
	v_cvt_pk_bf16_f32 v116, v118, v119
	v_mfma_f32_32x32x16_bf16 v[66:81], v[166:169], v[134:137], v[66:81]
	ds_read_b128 v[94:97], v248 offset:55360
	ds_read_b128 v[224:227], v248 offset:59968
	v_exp_f32_e32 v122, v122
	v_exp_f32_e32 v123, v123
	v_add_f32_e32 v246, v120, v246
	v_add_f32_e32 v246, v121, v246
	v_cvt_pk_bf16_f32 v117, v120, v121
	v_mfma_f32_32x32x16_bf16 v[34:49], v[182:185], v[134:137], v[34:49]
	ds_read_b128 v[212:215], v248 offset:55392
	ds_read_b128 v[242:245], v248 offset:60000
	v_exp_f32_e32 v124, v124
	v_exp_f32_e32 v125, v125
	v_add_f32_e32 v246, v122, v246
	v_add_f32_e32 v246, v123, v246
	v_cvt_pk_bf16_f32 v118, v122, v123
	v_mfma_f32_32x32x16_bf16 v[66:81], v[170:173], v[138:141], v[66:81]
	s_cmp_ge_u32 s11, s16
	s_cbranch_scc1 .Lattn_fx_skipw4
	s_waitcnt vmcnt(2)
	ds_write_b128 v192, v[154:157]
	ds_write_b128 v204, v[158:161] offset:9216
.Lattn_fx_skipw4:
	v_exp_f32_e32 v126, v126
	v_exp_f32_e32 v127, v127
	v_add_f32_e32 v246, v124, v246
	v_add_f32_e32 v246, v125, v246
	v_cvt_pk_bf16_f32 v119, v124, v125
	v_mfma_f32_32x32x16_bf16 v[34:49], v[186:189], v[138:141], v[34:49]
	v_exp_f32_e32 v128, v128
	v_exp_f32_e32 v129, v129
	v_add_f32_e32 v246, v126, v246
	v_add_f32_e32 v246, v127, v246
	v_cvt_pk_bf16_f32 v120, v126, v127
	v_mfma_f32_32x32x16_bf16 v[66:81], v[174:177], v[142:145], v[66:81]
	v_exp_f32_e32 v98, v98
	v_exp_f32_e32 v99, v99
	v_add_f32_e32 v246, v128, v246
	v_add_f32_e32 v246, v129, v246
	v_cvt_pk_bf16_f32 v121, v128, v129
	v_mfma_f32_32x32x16_bf16 v[34:49], v[82:85], v[142:145], v[34:49]
	s_waitcnt lgkmcnt(0)
	v_mfma_f32_32x32x16_bf16 v[18:33], v[86:89], v[114:117], v[18:33]
	s_barrier
	ds_read_b128 v[162:165], v193
	ds_read_b128 v[178:181], v193 offset:4608
	v_exp_f32_e32 v100, v100
	v_exp_f32_e32 v101, v101
	v_add_f32_e32 v247, v98, v99
	v_cvt_pk_bf16_f32 v122, v98, v99
	v_exp_f32_e32 v102, v102
	v_exp_f32_e32 v103, v103
	v_add_f32_e32 v247, v100, v247
	v_add_f32_e32 v247, v101, v247
	v_cvt_pk_bf16_f32 v123, v100, v101
	v_mfma_f32_32x32x16_bf16 v[2:17], v[216:219], v[114:117], v[2:17]
	ds_read_b128 v[166:169], v193 offset:32
	ds_read_b128 v[182:185], v193 offset:4640
	v_exp_f32_e32 v104, v104
	v_exp_f32_e32 v105, v105
	v_add_f32_e32 v247, v102, v247
	v_add_f32_e32 v247, v103, v247
	v_cvt_pk_bf16_f32 v124, v102, v103
	v_mfma_f32_32x32x16_bf16 v[18:33], v[90:93], v[118:121], v[18:33]
	ds_read_b128 v[170:173], v193 offset:64
	ds_read_b128 v[186:189], v193 offset:4672
	v_exp_f32_e32 v106, v106
	v_exp_f32_e32 v107, v107
	v_add_f32_e32 v247, v104, v247
	v_add_f32_e32 v247, v105, v247
	v_cvt_pk_bf16_f32 v125, v104, v105
	v_mfma_f32_32x32x16_bf16 v[2:17], v[220:223], v[118:121], v[2:17]
	ds_read_b128 v[174:177], v193 offset:96
	ds_read_b128 v[82:85], v193 offset:4704
	v_exp_f32_e32 v108, v108
	v_exp_f32_e32 v109, v109
	v_add_f32_e32 v247, v106, v247
	v_add_f32_e32 v247, v107, v247
	v_cvt_pk_bf16_f32 v126, v106, v107
	v_mfma_f32_32x32x16_bf16 v[18:33], v[94:97], v[122:125], v[18:33]
	v_exp_f32_e32 v110, v110
	v_exp_f32_e32 v111, v111
	v_add_f32_e32 v247, v108, v247
	v_add_f32_e32 v247, v109, v247
	v_cvt_pk_bf16_f32 v127, v108, v109
	v_mfma_f32_32x32x16_bf16 v[2:17], v[224:227], v[122:125], v[2:17]
	v_exp_f32_e32 v112, v112
	v_exp_f32_e32 v113, v113
	v_add_f32_e32 v247, v110, v247
	v_add_f32_e32 v247, v111, v247
	v_cvt_pk_bf16_f32 v128, v110, v111
	v_cvt_pk_bf16_f32 v129, v112, v113
	v_add_f32_e32 v247, v112, v247
	v_add_f32_e32 v247, v113, v247
	v_mfma_f32_32x32x16_bf16 v[18:33], v[212:215], v[126:129], v[18:33]
	v_mfma_f32_32x32x16_bf16 v[2:17], v[242:245], v[126:129], v[2:17]
	v_add_f32_e32 v210, v210, v246
	v_add_f32_e32 v210, v210, v247
	s_add_i32 s10, s10, 2
	s_cmp_lt_u32 s11, s16
	s_cbranch_scc0 .Lattn_fx_exit1
	s_branch .Lattn_fx_top
